# P0 row loop: counted waits (vmcnt 7..4) so the next row's prefetch loads are no longer waited at the top of the current row; wait moved to the row hand-over
# speedup vs baseline: 1.0125x; 1.0040x over previous
.LBB0_21:
	s_or_b64 exec, exec, s[60:61]
	s_add_u32 s4, s4, s30
	v_lshl_add_u64 v[40:41], v[40:41], 0, s[28:29]
	s_addc_u32 s5, s5, s31
	s_andn2_b64 vcc, exec, s[52:53]
	s_mov_b32 s26, s34
	s_waitcnt vmcnt(4)
	v_mov_b32_e32 v30, v2
	v_mov_b32_e32 v31, v3
	v_mov_b32_e32 v32, v4
	v_mov_b32_e32 v33, v5
	v_mov_b32_e32 v26, v6
	v_mov_b32_e32 v27, v7
	v_mov_b32_e32 v28, v8
	v_mov_b32_e32 v29, v9
	v_mov_b32_e32 v22, v10
	v_mov_b32_e32 v23, v11
	v_mov_b32_e32 v24, v12
	v_mov_b32_e32 v25, v13
	v_mov_b32_e32 v18, v14
	s_waitcnt lgkmcnt(0)
	v_mov_b32_e32 v19, v15
	v_mov_b32_e32 v20, v16
	v_mov_b32_e32 v21, v17
	s_cbranch_vccz .LBB0_28

.LBB0_24:
	s_waitcnt vmcnt(7)
	v_mul_f32_e32 v43, v31, v31
	v_mul_f32_e32 v55, v33, v33
	v_fmac_f32_e32 v43, v30, v30
	v_fmac_f32_e32 v55, v32, v32
	v_add_f32_e32 v43, v43, v55
	s_waitcnt vmcnt(6)
	v_mul_f32_e32 v55, v27, v27
	v_mul_f32_e32 v56, v29, v29
	v_fmac_f32_e32 v55, v26, v26
	v_fmac_f32_e32 v56, v28, v28
	v_add_f32_e32 v55, v55, v56
	v_add_f32_e32 v43, v43, v55
	s_waitcnt vmcnt(5)
	v_mul_f32_e32 v55, v23, v23
	v_mul_f32_e32 v56, v25, v25
	v_fmac_f32_e32 v55, v22, v22
	v_fmac_f32_e32 v56, v24, v24
	v_add_f32_e32 v55, v55, v56
	v_add_f32_e32 v43, v43, v55
	s_waitcnt vmcnt(4)
	v_mul_f32_e32 v55, v19, v19
	v_mul_f32_e32 v56, v21, v21
	v_fmac_f32_e32 v55, v18, v18
	v_fmac_f32_e32 v56, v20, v20
	v_add_f32_e32 v55, v55, v56
	v_add_f32_e32 v43, v43, v55
	ds_bpermute_b32 v55, v1, v43
	s_waitcnt lgkmcnt(0)
	v_add_f32_e32 v43, v43, v55
	ds_bpermute_b32 v55, v46, v43
	s_waitcnt lgkmcnt(0)
	v_add_f32_e32 v43, v43, v55
	ds_bpermute_b32 v55, v47, v43
	s_waitcnt lgkmcnt(0)
	v_add_f32_e32 v43, v43, v55
	ds_bpermute_b32 v55, v48, v43
	s_waitcnt lgkmcnt(0)
	v_add_f32_e32 v43, v43, v55
	ds_bpermute_b32 v55, v49, v43
	s_waitcnt lgkmcnt(0)
	v_add_f32_e32 v43, v43, v55
	ds_bpermute_b32 v55, v50, v43
	s_waitcnt lgkmcnt(0)
	v_add_f32_e32 v43, v43, v55
	s_and_saveexec_b64 s[60:61], s[6:7]
	s_cbranch_execz .LBB0_26
	s_add_u32 s88, s72, s4
	s_addc_u32 s89, s73, s5
	global_store_dword v35, v43, s[88:89]

.Lp0_nopf:
	s_waitcnt vmcnt(0)
	s_branch .LBB0_24
